# diff far body: next-tile LDS write and global prefetch moved mid-body, barrier at body top, exp block 0 hidden under second QK chain
# speedup vs baseline: 1.0106x; 1.0106x over previous
.LBB0_1037:
	s_add_i32 s26, s27, 0x8c00
	s_cmp_lg_u32 s27, 0x11800
	s_cselect_b32 s26, s26, 0
	s_add_i32 s30, s21, s12
	s_addk_i32 s30, 0x99
	s_cmpk_gt_u32 s30, 0x112
	s_cbranch_scc1 .Lfar_p1
	s_cmpk_eq_i32 s12, 0x1fc0
	s_cbranch_scc1 .LBB0_1039
	s_add_i32 s28, s26, 0
	v_add_u32_e32 v80, s28, v194
	v_add3_u32 v82, s28, v192, v193
	v_add_u32_e32 v81, v80, v197
	v_add_u32_e32 v80, v80, v196
	s_waitcnt vmcnt(2)
	ds_write_b128 v82, v[128:131]
	s_waitcnt vmcnt(1)
	ds_write_b128 v80, v[132:135] offset:17408
	s_waitcnt vmcnt(0)
	ds_write_b128 v81, v[136:139] offset:17408

.LBB0_1041:
	v_add_u32_e32 v175, s27, v198
	s_add_i32 s30, s21, s12
	ds_read_b128 v[178:181], v175
	s_add_i32 s28, s30, 63
	s_cmpk_gt_i32 s28, 0xffa5
	s_cselect_b64 vcc, -1, 0
	s_sub_i32 s28, s30, 31
	s_cmpk_lt_i32 s28, 0x5b
	s_cselect_b64 s[28:29], -1, 0
	v_cndmask_b32_e64 v80, v205, -v143, s[28:29]
	v_cndmask_b32_e32 v80, v204, v80, vcc
	v_mov_b32_e32 v81, v80
	v_mov_b32_e32 v82, v80
	v_mov_b32_e32 v83, v80
	v_mov_b32_e32 v84, v80
	v_mov_b32_e32 v85, v80
	v_mov_b32_e32 v86, v80
	v_mov_b32_e32 v87, v80
	v_mov_b32_e32 v88, v80
	v_mov_b32_e32 v89, v80
	v_mov_b32_e32 v90, v80
	v_mov_b32_e32 v91, v80
	v_mov_b32_e32 v92, v80
	v_mov_b32_e32 v93, v80
	v_mov_b32_e32 v94, v80
	v_mov_b32_e32 v95, v80
	s_addk_i32 s30, 0x99
	s_cmpk_gt_u32 s30, 0x112
	s_waitcnt lgkmcnt(0)
	v_mfma_f32_32x32x16_bf16 v[96:111], v[178:181], v[112:115], v[80:95]
	ds_read_b128 v[178:181], v175 offset:4608
	s_waitcnt lgkmcnt(0)
	v_mfma_f32_32x32x16_bf16 v[80:95], v[178:181], v[112:115], v[80:95]
	ds_read_b128 v[178:181], v175 offset:32
	s_waitcnt lgkmcnt(0)
	v_mfma_f32_32x32x16_bf16 v[96:111], v[178:181], v[116:119], v[96:111]
	ds_read_b128 v[178:181], v175 offset:4640
	s_waitcnt lgkmcnt(0)
	v_mfma_f32_32x32x16_bf16 v[80:95], v[178:181], v[116:119], v[80:95]
	ds_read_b128 v[178:181], v175 offset:64
	s_waitcnt lgkmcnt(0)
	v_mfma_f32_32x32x16_bf16 v[96:111], v[178:181], v[120:123], v[96:111]
	ds_read_b128 v[178:181], v175 offset:4672
	s_waitcnt lgkmcnt(0)
	v_mfma_f32_32x32x16_bf16 v[80:95], v[178:181], v[120:123], v[80:95]
	ds_read_b128 v[178:181], v175 offset:96
	s_waitcnt lgkmcnt(0)
	v_mfma_f32_32x32x16_bf16 v[96:111], v[178:181], v[124:127], v[96:111]
	ds_read_b128 v[178:181], v175 offset:4704
	s_waitcnt lgkmcnt(0)
	v_mfma_f32_32x32x16_bf16 v[80:95], v[178:181], v[124:127], v[80:95]
	s_cbranch_scc1 .LBB0_1036
	v_add_u32_e32 v178, s12, v167
	v_ashrrev_i32_e32 v179, 31, v178
	v_lshl_add_u64 v[182:183], v[178:179], 2, s[8:9]
	global_load_dwordx4 v[178:181], v[182:183], off offset:80
	global_load_dwordx4 v[206:209], v[182:183], off offset:64
	global_load_dwordx4 v[210:213], v[182:183], off offset:16
	global_load_dwordx4 v[214:217], v[182:183], off
	global_load_dwordx4 v[230:233], v[182:183], off offset:208
	global_load_dwordx4 v[236:239], v[182:183], off offset:192
	global_load_dwordx4 v[240:243], v[182:183], off offset:144
	global_load_dwordx4 v[244:247], v[182:183], off offset:128
	s_waitcnt vmcnt(7)
	v_pk_add_f32 v[110:111], v[110:111], v[180:181]
	s_waitcnt vmcnt(6)
	v_pk_add_f32 v[106:107], v[106:107], v[208:209]
	s_waitcnt vmcnt(5)
	v_pk_add_f32 v[102:103], v[102:103], v[212:213]
	s_waitcnt vmcnt(4)
	v_pk_add_f32 v[98:99], v[98:99], v[216:217]
	v_pk_add_f32 v[108:109], v[108:109], v[178:179]
	v_pk_add_f32 v[104:105], v[104:105], v[206:207]
	v_pk_add_f32 v[100:101], v[100:101], v[210:211]
	v_pk_add_f32 v[96:97], v[96:97], v[214:215]
	s_waitcnt vmcnt(3)
	v_pk_add_f32 v[94:95], v[94:95], v[232:233]
	s_waitcnt vmcnt(2)
	v_pk_add_f32 v[90:91], v[90:91], v[238:239]
	s_waitcnt vmcnt(1)
	v_pk_add_f32 v[86:87], v[86:87], v[242:243]
	s_waitcnt vmcnt(0)
	v_pk_add_f32 v[82:83], v[82:83], v[246:247]
	v_pk_add_f32 v[92:93], v[92:93], v[230:231]
	v_pk_add_f32 v[88:89], v[88:89], v[236:237]
	v_pk_add_f32 v[84:85], v[84:85], v[240:241]
	v_pk_add_f32 v[80:81], v[80:81], v[244:245]
	s_branch .LBB0_1036
.Lfar_p1:
	s_waitcnt lgkmcnt(0)
	s_barrier
	v_add_u32_e32 v175, s27, v198
	ds_read_b128 v[178:181], v175
	ds_read_b128 v[206:209], v175 offset:32
	ds_read_b128 v[210:213], v175 offset:64
	ds_read_b128 v[214:217], v175 offset:96
	ds_read_b128 v[230:233], v175 offset:4608
	ds_read_b128 v[236:239], v175 offset:4640
	s_cmp_gt_i32 s30, -1
	s_cselect_b64 vcc, -1, 0
	v_mov_b32_e32 v240, s68
	v_mov_b32_e32 v241, s68
	v_mov_b32_e32 v242, s68
	v_mov_b32_e32 v243, s68
	v_cndmask_b32_e32 v80, v204, v205, vcc
	v_mov_b32_e32 v81, v80
	v_mov_b32_e32 v82, v80
	v_mov_b32_e32 v83, v80
	v_mov_b32_e32 v84, v80
	v_mov_b32_e32 v85, v80
	v_mov_b32_e32 v86, v80
	v_mov_b32_e32 v87, v80
	v_mov_b32_e32 v88, v80
	v_mov_b32_e32 v89, v80
	v_mov_b32_e32 v90, v80
	v_mov_b32_e32 v91, v80
	v_mov_b32_e32 v92, v80
	v_mov_b32_e32 v93, v80
	v_mov_b32_e32 v94, v80
	v_mov_b32_e32 v95, v80
	s_nop 0
	s_waitcnt lgkmcnt(5)
	v_mfma_f32_32x32x16_bf16 v[96:111], v[178:181], v[112:115], v[80:95]
	ds_read_b128 v[178:181], v175 offset:4672
	s_waitcnt lgkmcnt(5)
	v_mfma_f32_32x32x16_bf16 v[96:111], v[206:209], v[116:119], v[96:111]
	ds_read_b128 v[206:209], v175 offset:4704
	s_waitcnt lgkmcnt(5)
	v_mfma_f32_32x32x16_bf16 v[96:111], v[210:213], v[120:123], v[96:111]
	ds_read_b128 v[210:213], v175 offset:17408
	s_waitcnt lgkmcnt(5)
	v_mfma_f32_32x32x16_bf16 v[96:111], v[214:217], v[124:127], v[96:111]
	ds_read_b128 v[214:217], v175 offset:22016
	s_waitcnt lgkmcnt(5)
	v_mfma_f32_32x32x16_bf16 v[80:95], v[230:233], v[112:115], v[80:95]
	ds_read_b128 v[230:233], v175 offset:26624
	s_waitcnt lgkmcnt(5)
	v_mfma_f32_32x32x16_bf16 v[80:95], v[236:239], v[116:119], v[80:95]
	ds_read_b128 v[236:239], v175 offset:31232
	v_add_u32_e32 v185, s26, v194
	v_add3_u32 v184, s26, v192, v193
	v_add_u32_e32 v218, v185, v197
	v_add_u32_e32 v185, v185, v196
	s_nop 0
	v_exp_f32_e32 v96, v96
	v_exp_f32_e32 v97, v97
	v_exp_f32_e32 v98, v98
	s_waitcnt lgkmcnt(5)
	v_mfma_f32_32x32x16_bf16 v[80:95], v[178:181], v[120:123], v[80:95]
	ds_read_b128 v[178:181], v175 offset:17440
	v_exp_f32_e32 v99, v99
	v_exp_f32_e32 v100, v100
	v_exp_f32_e32 v101, v101
	s_waitcnt lgkmcnt(5)
	v_mfma_f32_32x32x16_bf16 v[80:95], v[206:209], v[124:127], v[80:95]
	ds_read_b128 v[206:209], v175 offset:22048
	v_exp_f32_e32 v102, v102
	v_exp_f32_e32 v103, v103
	v_cvt_pk_bf16_f32 v96, v96, v97
	v_cvt_pk_bf16_f32 v97, v98, v99
	v_cvt_pk_bf16_f32 v98, v100, v101
	v_cvt_pk_bf16_f32 v99, v102, v103
	s_nop 1
	v_mfma_f32_32x32x16_bf16 v[64:79], v[240:243], v[96:99], v[64:79]
	v_exp_f32_e32 v104, v104
	v_exp_f32_e32 v105, v105
	v_exp_f32_e32 v106, v106
	s_waitcnt lgkmcnt(5)
	v_mfma_f32_32x32x16_bf16 v[48:63], v[210:213], v[96:99], v[48:63]
	ds_read_b128 v[210:213], v175 offset:26656
	s_waitcnt vmcnt(2)
	ds_write_b128 v184, v[128:131]
	v_exp_f32_e32 v107, v107
	v_exp_f32_e32 v108, v108
	v_exp_f32_e32 v109, v109
	s_waitcnt lgkmcnt(6)
	v_mfma_f32_32x32x16_bf16 v[32:47], v[214:217], v[96:99], v[32:47]
	ds_read_b128 v[214:217], v175 offset:31264
	s_waitcnt vmcnt(1)
	ds_write_b128 v185, v[132:135] offset:17408
	v_exp_f32_e32 v110, v110
	v_exp_f32_e32 v111, v111
	v_cvt_pk_bf16_f32 v104, v104, v105
	s_waitcnt lgkmcnt(7)
	v_mfma_f32_32x32x16_bf16 v[16:31], v[230:233], v[96:99], v[16:31]
	ds_read_b128 v[230:233], v175 offset:17472
	s_waitcnt vmcnt(0)
	ds_write_b128 v218, v[136:139] offset:17408
	v_cvt_pk_bf16_f32 v105, v106, v107
	v_cvt_pk_bf16_f32 v106, v108, v109
	v_cvt_pk_bf16_f32 v107, v110, v111
	s_waitcnt lgkmcnt(8)
	v_mfma_f32_32x32x16_bf16 v[0:15], v[236:239], v[96:99], v[0:15]
	ds_read_b128 v[236:239], v175 offset:22080
	v_mfma_f32_32x32x16_bf16 v[64:79], v[240:243], v[104:107], v[64:79]
	v_exp_f32_e32 v80, v80
	v_exp_f32_e32 v81, v81
	v_exp_f32_e32 v82, v82
	s_waitcnt lgkmcnt(8)
	v_mfma_f32_32x32x16_bf16 v[48:63], v[178:181], v[104:107], v[48:63]
	ds_read_b128 v[178:181], v175 offset:26688
	v_exp_f32_e32 v83, v83
	v_exp_f32_e32 v84, v84
	v_exp_f32_e32 v85, v85
	s_waitcnt lgkmcnt(8)
	v_mfma_f32_32x32x16_bf16 v[32:47], v[206:209], v[104:107], v[32:47]
	ds_read_b128 v[206:209], v175 offset:31296
	v_exp_f32_e32 v86, v86
	v_exp_f32_e32 v87, v87
	v_cvt_pk_bf16_f32 v80, v80, v81
	s_waitcnt lgkmcnt(8)
	v_mfma_f32_32x32x16_bf16 v[16:31], v[210:213], v[104:107], v[16:31]
	ds_read_b128 v[210:213], v175 offset:17504
	v_cvt_pk_bf16_f32 v81, v82, v83
	v_cvt_pk_bf16_f32 v82, v84, v85
	v_cvt_pk_bf16_f32 v83, v86, v87
	s_waitcnt lgkmcnt(7)
	v_mfma_f32_32x32x16_bf16 v[0:15], v[214:217], v[104:107], v[0:15]
	ds_read_b128 v[214:217], v175 offset:22112
	v_mfma_f32_32x32x16_bf16 v[64:79], v[240:243], v[80:83], v[64:79]
	v_exp_f32_e32 v88, v88
	v_exp_f32_e32 v89, v89
	v_exp_f32_e32 v90, v90
	s_waitcnt lgkmcnt(6)
	v_mfma_f32_32x32x16_bf16 v[48:63], v[230:233], v[80:83], v[48:63]
	ds_read_b128 v[230:233], v175 offset:26720
	v_exp_f32_e32 v91, v91
	v_exp_f32_e32 v92, v92
	v_exp_f32_e32 v93, v93
	s_waitcnt lgkmcnt(5)
	v_mfma_f32_32x32x16_bf16 v[32:47], v[236:239], v[80:83], v[32:47]
	ds_read_b128 v[236:239], v175 offset:31328
	v_exp_f32_e32 v94, v94
	v_exp_f32_e32 v95, v95
	v_cvt_pk_bf16_f32 v88, v88, v89
	s_cmpk_gt_u32 s13, 0x7d
	s_cbranch_scc1 .Lfar_p1_noload
	global_load_dwordx4 v[128:131], v[190:191], off
	global_load_dwordx4 v[132:135], v[188:189], off
	global_load_dwordx4 v[136:139], v[186:187], off
.Lfar_p1_noload:
	s_waitcnt lgkmcnt(5)
	v_mfma_f32_32x32x16_bf16 v[16:31], v[178:181], v[80:83], v[16:31]
	v_cvt_pk_bf16_f32 v89, v90, v91
	v_cvt_pk_bf16_f32 v90, v92, v93
	v_cvt_pk_bf16_f32 v91, v94, v95
	s_waitcnt lgkmcnt(4)
	v_mfma_f32_32x32x16_bf16 v[0:15], v[206:209], v[80:83], v[0:15]
	v_mfma_f32_32x32x16_bf16 v[64:79], v[240:243], v[88:91], v[64:79]
	s_add_i32 s12, s12, 64
	s_add_i32 s13, s13, 1
	s_waitcnt lgkmcnt(3)
	v_mfma_f32_32x32x16_bf16 v[48:63], v[210:213], v[88:91], v[48:63]
	v_lshl_add_u64 v[186:187], v[186:187], 0, s[72:73]
	s_waitcnt lgkmcnt(2)
	v_mfma_f32_32x32x16_bf16 v[32:47], v[214:217], v[88:91], v[32:47]
	v_lshl_add_u64 v[188:189], v[188:189], 0, s[72:73]
	s_waitcnt lgkmcnt(1)
	v_mfma_f32_32x32x16_bf16 v[16:31], v[230:233], v[88:91], v[16:31]
	v_lshl_add_u64 v[190:191], v[190:191], 0, s[0:1]
	s_mov_b32 s27, s26
	s_waitcnt lgkmcnt(0)
	v_mfma_f32_32x32x16_bf16 v[0:15], v[236:239], v[88:91], v[0:15]
	s_cmpk_lg_i32 s12, 0x2000
	s_cbranch_scc0 .LBB0_1043
	s_branch .LBB0_1037

.LBB0_1060:
	s_add_i32 s12, s13, 0x8c00
	s_cmp_lg_u32 s13, 0x11800
	s_cselect_b32 s12, s12, 0
	s_add_i32 s24, s21, s10
	s_addk_i32 s24, 0x99
	s_cmpk_gt_u32 s24, 0x112
	s_cbranch_scc1 .Lfar_p2
	s_cmpk_eq_i32 s10, 0x1fc0
	s_cbranch_scc1 .LBB0_1062
	s_add_i32 s22, s12, 0
	v_add_u32_e32 v80, s22, v194
	v_add3_u32 v82, s22, v192, v193
	v_add_u32_e32 v81, v80, v197
	v_add_u32_e32 v80, v80, v196
	s_waitcnt vmcnt(2)
	ds_write_b128 v82, v[128:131]
	s_waitcnt vmcnt(1)
	ds_write_b128 v80, v[132:135] offset:17408
	s_waitcnt vmcnt(0)
	ds_write_b128 v81, v[136:139] offset:17408

.LBB0_1064:
	v_add_u32_e32 v169, s13, v198
	s_add_i32 s24, s21, s10
	ds_read_b128 v[178:181], v169
	s_add_i32 s22, s24, 63
	s_cmpk_gt_i32 s22, 0xffa5
	s_cselect_b64 vcc, -1, 0
	s_sub_i32 s22, s24, 31
	s_cmpk_lt_i32 s22, 0x5b
	s_cselect_b64 s[22:23], -1, 0
	v_cndmask_b32_e64 v80, v205, -v143, s[22:23]
	v_cndmask_b32_e32 v80, v204, v80, vcc
	v_mov_b32_e32 v81, v80
	v_mov_b32_e32 v82, v80
	v_mov_b32_e32 v83, v80
	v_mov_b32_e32 v84, v80
	v_mov_b32_e32 v85, v80
	v_mov_b32_e32 v86, v80
	v_mov_b32_e32 v87, v80
	v_mov_b32_e32 v88, v80
	v_mov_b32_e32 v89, v80
	v_mov_b32_e32 v90, v80
	v_mov_b32_e32 v91, v80
	v_mov_b32_e32 v92, v80
	v_mov_b32_e32 v93, v80
	v_mov_b32_e32 v94, v80
	v_mov_b32_e32 v95, v80
	s_addk_i32 s24, 0x99
	s_cmpk_gt_u32 s24, 0x112
	s_waitcnt lgkmcnt(0)
	v_mfma_f32_32x32x16_bf16 v[96:111], v[178:181], v[112:115], v[80:95]
	ds_read_b128 v[178:181], v169 offset:4608
	s_waitcnt lgkmcnt(0)
	v_mfma_f32_32x32x16_bf16 v[80:95], v[178:181], v[112:115], v[80:95]
	ds_read_b128 v[178:181], v169 offset:32
	s_waitcnt lgkmcnt(0)
	v_mfma_f32_32x32x16_bf16 v[96:111], v[178:181], v[116:119], v[96:111]
	ds_read_b128 v[178:181], v169 offset:4640
	s_waitcnt lgkmcnt(0)
	v_mfma_f32_32x32x16_bf16 v[80:95], v[178:181], v[116:119], v[80:95]
	ds_read_b128 v[178:181], v169 offset:64
	s_waitcnt lgkmcnt(0)
	v_mfma_f32_32x32x16_bf16 v[96:111], v[178:181], v[120:123], v[96:111]
	ds_read_b128 v[178:181], v169 offset:4672
	s_waitcnt lgkmcnt(0)
	v_mfma_f32_32x32x16_bf16 v[80:95], v[178:181], v[120:123], v[80:95]
	ds_read_b128 v[178:181], v169 offset:96
	s_waitcnt lgkmcnt(0)
	v_mfma_f32_32x32x16_bf16 v[96:111], v[178:181], v[124:127], v[96:111]
	ds_read_b128 v[178:181], v169 offset:4704
	s_waitcnt lgkmcnt(0)
	v_mfma_f32_32x32x16_bf16 v[80:95], v[178:181], v[124:127], v[80:95]
	s_cbranch_scc1 .LBB0_1059
	v_add_u32_e32 v178, s10, v167
	v_ashrrev_i32_e32 v179, 31, v178
	v_lshl_add_u64 v[182:183], v[178:179], 2, s[8:9]
	global_load_dwordx4 v[178:181], v[182:183], off offset:80
	global_load_dwordx4 v[186:189], v[182:183], off offset:64
	global_load_dwordx4 v[206:209], v[182:183], off offset:16
	global_load_dwordx4 v[210:213], v[182:183], off
	global_load_dwordx4 v[214:217], v[182:183], off offset:208
	global_load_dwordx4 v[230:233], v[182:183], off offset:192
	global_load_dwordx4 v[236:239], v[182:183], off offset:144
	global_load_dwordx4 v[240:243], v[182:183], off offset:128
	s_waitcnt vmcnt(7)
	v_pk_add_f32 v[110:111], v[110:111], v[180:181]
	s_waitcnt vmcnt(6)
	v_pk_add_f32 v[106:107], v[106:107], v[188:189]
	s_waitcnt vmcnt(5)
	v_pk_add_f32 v[102:103], v[102:103], v[208:209]
	s_waitcnt vmcnt(4)
	v_pk_add_f32 v[98:99], v[98:99], v[212:213]
	v_pk_add_f32 v[108:109], v[108:109], v[178:179]
	v_pk_add_f32 v[104:105], v[104:105], v[186:187]
	v_pk_add_f32 v[100:101], v[100:101], v[206:207]
	v_pk_add_f32 v[96:97], v[96:97], v[210:211]
	s_waitcnt vmcnt(3)
	v_pk_add_f32 v[94:95], v[94:95], v[216:217]
	s_waitcnt vmcnt(2)
	v_pk_add_f32 v[90:91], v[90:91], v[232:233]
	s_waitcnt vmcnt(1)
	v_pk_add_f32 v[86:87], v[86:87], v[238:239]
	s_waitcnt vmcnt(0)
	v_pk_add_f32 v[82:83], v[82:83], v[242:243]
	v_pk_add_f32 v[92:93], v[92:93], v[214:215]
	v_pk_add_f32 v[88:89], v[88:89], v[230:231]
	v_pk_add_f32 v[84:85], v[84:85], v[236:237]
	v_pk_add_f32 v[80:81], v[80:81], v[240:241]
	s_branch .LBB0_1059
.Lfar_p2:
	s_waitcnt lgkmcnt(0)
	s_barrier
	v_add_u32_e32 v169, s13, v198
	ds_read_b128 v[178:181], v169
	ds_read_b128 v[206:209], v169 offset:32
	ds_read_b128 v[210:213], v169 offset:64
	ds_read_b128 v[214:217], v169 offset:96
	ds_read_b128 v[230:233], v169 offset:4608
	ds_read_b128 v[236:239], v169 offset:4640
	s_cmp_gt_i32 s24, -1
	s_cselect_b64 vcc, -1, 0
	v_mov_b32_e32 v240, s68
	v_mov_b32_e32 v241, s68
	v_mov_b32_e32 v242, s68
	v_mov_b32_e32 v243, s68
	v_cndmask_b32_e32 v80, v204, v205, vcc
	v_mov_b32_e32 v81, v80
	v_mov_b32_e32 v82, v80
	v_mov_b32_e32 v83, v80
	v_mov_b32_e32 v84, v80
	v_mov_b32_e32 v85, v80
	v_mov_b32_e32 v86, v80
	v_mov_b32_e32 v87, v80
	v_mov_b32_e32 v88, v80
	v_mov_b32_e32 v89, v80
	v_mov_b32_e32 v90, v80
	v_mov_b32_e32 v91, v80
	v_mov_b32_e32 v92, v80
	v_mov_b32_e32 v93, v80
	v_mov_b32_e32 v94, v80
	v_mov_b32_e32 v95, v80
	s_nop 0
	s_waitcnt lgkmcnt(5)
	v_mfma_f32_32x32x16_bf16 v[96:111], v[178:181], v[112:115], v[80:95]
	ds_read_b128 v[178:181], v169 offset:4672
	s_waitcnt lgkmcnt(5)
	v_mfma_f32_32x32x16_bf16 v[96:111], v[206:209], v[116:119], v[96:111]
	ds_read_b128 v[206:209], v169 offset:4704
	s_waitcnt lgkmcnt(5)
	v_mfma_f32_32x32x16_bf16 v[96:111], v[210:213], v[120:123], v[96:111]
	ds_read_b128 v[210:213], v169 offset:17408
	s_waitcnt lgkmcnt(5)
	v_mfma_f32_32x32x16_bf16 v[96:111], v[214:217], v[124:127], v[96:111]
	ds_read_b128 v[214:217], v169 offset:22016
	s_waitcnt lgkmcnt(5)
	v_mfma_f32_32x32x16_bf16 v[80:95], v[230:233], v[112:115], v[80:95]
	ds_read_b128 v[230:233], v169 offset:26624
	s_waitcnt lgkmcnt(5)
	v_mfma_f32_32x32x16_bf16 v[80:95], v[236:239], v[116:119], v[80:95]
	ds_read_b128 v[236:239], v169 offset:31232
	v_add_u32_e32 v185, s12, v194
	v_add3_u32 v184, s12, v192, v193
	v_add_u32_e32 v218, v185, v197
	v_add_u32_e32 v185, v185, v196
	s_nop 0
	v_exp_f32_e32 v96, v96
	v_exp_f32_e32 v97, v97
	v_exp_f32_e32 v98, v98
	s_waitcnt lgkmcnt(5)
	v_mfma_f32_32x32x16_bf16 v[80:95], v[178:181], v[120:123], v[80:95]
	ds_read_b128 v[178:181], v169 offset:17440
	v_exp_f32_e32 v99, v99
	v_exp_f32_e32 v100, v100
	v_exp_f32_e32 v101, v101
	s_waitcnt lgkmcnt(5)
	v_mfma_f32_32x32x16_bf16 v[80:95], v[206:209], v[124:127], v[80:95]
	ds_read_b128 v[206:209], v169 offset:22048
	v_exp_f32_e32 v102, v102
	v_exp_f32_e32 v103, v103
	v_cvt_pk_bf16_f32 v96, v96, v97
	v_cvt_pk_bf16_f32 v97, v98, v99
	v_cvt_pk_bf16_f32 v98, v100, v101
	v_cvt_pk_bf16_f32 v99, v102, v103
	s_nop 1
	v_mfma_f32_32x32x16_bf16 v[64:79], v[240:243], v[96:99], v[64:79]
	v_exp_f32_e32 v104, v104
	v_exp_f32_e32 v105, v105
	v_exp_f32_e32 v106, v106
	s_waitcnt lgkmcnt(5)
	v_mfma_f32_32x32x16_bf16 v[48:63], v[210:213], v[96:99], v[48:63]
	ds_read_b128 v[210:213], v169 offset:26656
	s_waitcnt vmcnt(2)
	ds_write_b128 v184, v[128:131]
	v_exp_f32_e32 v107, v107
	v_exp_f32_e32 v108, v108
	v_exp_f32_e32 v109, v109
	s_waitcnt lgkmcnt(6)
	v_mfma_f32_32x32x16_bf16 v[32:47], v[214:217], v[96:99], v[32:47]
	ds_read_b128 v[214:217], v169 offset:31264
	s_waitcnt vmcnt(1)
	ds_write_b128 v185, v[132:135] offset:17408
	v_exp_f32_e32 v110, v110
	v_exp_f32_e32 v111, v111
	v_cvt_pk_bf16_f32 v104, v104, v105
	s_waitcnt lgkmcnt(7)
	v_mfma_f32_32x32x16_bf16 v[16:31], v[230:233], v[96:99], v[16:31]
	ds_read_b128 v[230:233], v169 offset:17472
	s_waitcnt vmcnt(0)
	ds_write_b128 v218, v[136:139] offset:17408
	v_cvt_pk_bf16_f32 v105, v106, v107
	v_cvt_pk_bf16_f32 v106, v108, v109
	v_cvt_pk_bf16_f32 v107, v110, v111
	s_waitcnt lgkmcnt(8)
	v_mfma_f32_32x32x16_bf16 v[0:15], v[236:239], v[96:99], v[0:15]
	ds_read_b128 v[236:239], v169 offset:22080
	v_mfma_f32_32x32x16_bf16 v[64:79], v[240:243], v[104:107], v[64:79]
	v_exp_f32_e32 v80, v80
	v_exp_f32_e32 v81, v81
	v_exp_f32_e32 v82, v82
	s_waitcnt lgkmcnt(8)
	v_mfma_f32_32x32x16_bf16 v[48:63], v[178:181], v[104:107], v[48:63]
	ds_read_b128 v[178:181], v169 offset:26688
	v_exp_f32_e32 v83, v83
	v_exp_f32_e32 v84, v84
	v_exp_f32_e32 v85, v85
	s_waitcnt lgkmcnt(8)
	v_mfma_f32_32x32x16_bf16 v[32:47], v[206:209], v[104:107], v[32:47]
	ds_read_b128 v[206:209], v169 offset:31296
	v_exp_f32_e32 v86, v86
	v_exp_f32_e32 v87, v87
	v_cvt_pk_bf16_f32 v80, v80, v81
	s_waitcnt lgkmcnt(8)
	v_mfma_f32_32x32x16_bf16 v[16:31], v[210:213], v[104:107], v[16:31]
	ds_read_b128 v[210:213], v169 offset:17504
	v_cvt_pk_bf16_f32 v81, v82, v83
	v_cvt_pk_bf16_f32 v82, v84, v85
	v_cvt_pk_bf16_f32 v83, v86, v87
	s_waitcnt lgkmcnt(7)
	v_mfma_f32_32x32x16_bf16 v[0:15], v[214:217], v[104:107], v[0:15]
	ds_read_b128 v[214:217], v169 offset:22112
	v_mfma_f32_32x32x16_bf16 v[64:79], v[240:243], v[80:83], v[64:79]
	v_exp_f32_e32 v88, v88
	v_exp_f32_e32 v89, v89
	v_exp_f32_e32 v90, v90
	s_waitcnt lgkmcnt(6)
	v_mfma_f32_32x32x16_bf16 v[48:63], v[230:233], v[80:83], v[48:63]
	ds_read_b128 v[230:233], v169 offset:26720
	v_exp_f32_e32 v91, v91
	v_exp_f32_e32 v92, v92
	v_exp_f32_e32 v93, v93
	s_waitcnt lgkmcnt(5)
	v_mfma_f32_32x32x16_bf16 v[32:47], v[236:239], v[80:83], v[32:47]
	ds_read_b128 v[236:239], v169 offset:31328
	v_exp_f32_e32 v94, v94
	v_exp_f32_e32 v95, v95
	v_cvt_pk_bf16_f32 v88, v88, v89
	s_cmpk_gt_u32 s11, 0x7d
	s_cbranch_scc1 .Lfar_p2_noload
	global_load_dwordx4 v[128:131], v[174:175], off
	global_load_dwordx4 v[132:135], v[172:173], off
	global_load_dwordx4 v[136:139], v[170:171], off
.Lfar_p2_noload:
	s_waitcnt lgkmcnt(5)
	v_mfma_f32_32x32x16_bf16 v[16:31], v[178:181], v[80:83], v[16:31]
	v_cvt_pk_bf16_f32 v89, v90, v91
	v_cvt_pk_bf16_f32 v90, v92, v93
	v_cvt_pk_bf16_f32 v91, v94, v95
	s_waitcnt lgkmcnt(4)
	v_mfma_f32_32x32x16_bf16 v[0:15], v[206:209], v[80:83], v[0:15]
	v_mfma_f32_32x32x16_bf16 v[64:79], v[240:243], v[88:91], v[64:79]
	s_add_i32 s10, s10, 64
	s_add_i32 s11, s11, 1
	s_waitcnt lgkmcnt(3)
	v_mfma_f32_32x32x16_bf16 v[48:63], v[210:213], v[88:91], v[48:63]
	v_lshl_add_u64 v[170:171], v[170:171], 0, s[72:73]
	s_waitcnt lgkmcnt(2)
	v_mfma_f32_32x32x16_bf16 v[32:47], v[214:217], v[88:91], v[32:47]
	v_lshl_add_u64 v[172:173], v[172:173], 0, s[72:73]
	s_waitcnt lgkmcnt(1)
	v_mfma_f32_32x32x16_bf16 v[16:31], v[230:233], v[88:91], v[16:31]
	v_lshl_add_u64 v[174:175], v[174:175], 0, s[0:1]
	s_mov_b32 s13, s12
	s_waitcnt lgkmcnt(0)
	v_mfma_f32_32x32x16_bf16 v[0:15], v[236:239], v[88:91], v[0:15]
	s_cmpk_lg_i32 s10, 0x2000
	s_cbranch_scc0 .LBB0_1019
	s_branch .LBB0_1060
